# v006 + swiglu GEMM epilogues of the two wave-halves no longer aligned (ALIGN_EPI barriers removed except on the last tile)
# baseline (speedup 1.0000x reference)
; #define PG8_STAGE(bufoff, gbase, voff) do { _Pragma("unroll") for (int _i = 0; _i < 2; ++_i) \
;         __builtin_amdgcn_global_load_lds((const unsigned*)((const char*)(gbase) + (voff)[_i]), (LAS unsigned*)(lds + (bufoff) + ldsw + _i * 8192), 16, 0, 0); } while (0)
; #define PG8_LDA(dst, b, h) do { _Pragma("unroll") for (int m = 0; m < 4; ++m) _Pragma("unroll") for (int k = 0; k < 2; ++k) dst[m][k] = *(const LAS bf16x8*)(lds + PG8_SA(b, h) + aoff + m * 2048 + k * 1024); } while (0)
; #define PG8_LDB(dst, b, h) do { _Pragma("unroll") for (int n = 0; n < 2; ++n) _Pragma("unroll") for (int k = 0; k < 2; ++k) dst[n][k] = *(const LAS bf16x8*)(lds + PG8_SB(b, h) + boff + n * 2048 + k * 1024); } while (0)
; #define PG8_MMA(ai, bj, At, Bt) do { __builtin_amdgcn_s_setprio(1); _Pragma("unroll") for (int m = 0; m < 4; ++m) _Pragma("unroll") for (int n = 0; n < 2; ++n) _Pragma("unroll") for (int k = 0; k < 2; ++k) \
;         acc[ai][bj][m][n] = __builtin_amdgcn_mfma_f32_16x16x32_bf16(Bt[n][k], At[m][k], acc[ai][bj][m][n], 0, 0, 0); __builtin_amdgcn_s_setprio(0); } while (0)
; #define PG8_BAR __builtin_amdgcn_s_barrier()
; template <class Epi>
; __device__ __forceinline__ void gemm_phase(LAS unsigned char* lds, const Gemm g, const Order& S, const Epi& E, const int tid) {
;     ...
;         for (int t = 0; t < nt; t += 2) {
;             const bool last = (t == nt - 2);
;             const char* a1 = cA + (size_t)(t + 1) * kstep;
;             const char* a2 = last ? nA : cA + (size_t)(t + 2) * kstep; const char* b2 = last ? nB : cB + (size_t)(t + 2) * kstep;
;             const char* a3 = a2 + kstep; const char* b3 = b2 + kstep;
;             PG8_LDB(B0, 0, 0); PG8_LDB(B1, 0, 1); PG8_SCHED; PG8_LDA(At, 0, 0); PG8_STAGE(PG8_SA(1, 1), a1 + hstep, voffA);
;             PG8_WAIT_V(8); PG8_WAIT_L(0); PG8_BAR; PG8_MMA(0, 0, At, B0); PG8_MMA(0, 1, At, B1); PG8_BAR; PG8_SCHED;
;             PG8_LDA(At, 0, 1); PG8_STAGE(PG8_SB(0, 0), b2, voffB); PG8_STAGE(PG8_SB(0, 1), b2 + hstep, voffB); PG8_STAGE(PG8_SA(0, 0), a2, voffA);
;             PG8_WAIT_V(8); PG8_WAIT_L(0); PG8_BAR; PG8_MMA(1, 0, At, B0); PG8_MMA(1, 1, At, B1); PG8_BAR; PG8_SCHED;
;             PG8_LDB(B0, 1, 0); PG8_LDB(B1, 1, 1); PG8_SCHED; PG8_LDA(At, 1, 0); PG8_STAGE(PG8_SA(0, 1), a2 + hstep, voffA);
;             PG8_WAIT_V(8); PG8_WAIT_L(0); PG8_BAR; PG8_MMA(0, 0, At, B0); PG8_MMA(0, 1, At, B1); PG8_BAR; PG8_SCHED;
.LBB0_319:
	s_add_u32 s22, s26, 0xfffc0080
	s_addc_u32 s23, s27, -1
	s_add_i32 s54, 0, 0x10000
	s_cmp_eq_u32 s53, 12
	s_cselect_b32 s31, s13, s23
	s_cselect_b32 s30, s49, s22
	v_add_u32_e32 v153, s54, v156
	s_cselect_b32 s23, s11, s52
	s_cselect_b32 s22, s50, s51
	s_add_i32 s56, 0, 0x14000
	ds_read_b128 v[130:133], v153
	ds_read_b128 v[134:137], v153 offset:1024
	ds_read_b128 v[158:161], v153 offset:2048
	ds_read_b128 v[162:165], v153 offset:3072
	v_add_u32_e32 v153, s56, v156
	ds_read_b128 v[166:169], v153
	ds_read_b128 v[170:173], v153 offset:1024
	ds_read_b128 v[174:177], v153 offset:2048
	ds_read_b128 v[192:195], v153 offset:3072
	v_lshl_add_u64 v[178:179], s[26:27], 0, v[146:147]
	s_add_i32 m0, s37, 0xc000
	ds_read_b128 v[200:203], v152
	ds_read_b128 v[204:207], v152 offset:1024
	ds_read_b128 v[220:223], v152 offset:2048
	ds_read_b128 v[224:227], v152 offset:3072
	ds_read_b128 v[228:231], v152 offset:4096
	ds_read_b128 v[232:235], v152 offset:5120
	ds_read_b128 v[236:239], v152 offset:6144
	ds_read_b128 v[240:243], v152 offset:7168
	global_load_lds_dwordx4 v[178:179], off
	v_lshl_add_u64 v[178:179], s[26:27], 0, v[148:149]
	s_add_i32 m0, s37, 0xe000
	s_nop 0
	global_load_lds_dwordx4 v[178:179], off
	s_waitcnt vmcnt(8)
	s_waitcnt lgkmcnt(0)
	s_barrier
	s_setprio 1
	s_waitcnt lgkmcnt(0)
	v_mfma_f32_16x16x32_bf16 v[118:121], v[130:133], v[200:203], v[118:121]
	v_mfma_f32_16x16x32_bf16 v[114:117], v[158:161], v[200:203], v[114:117]
	v_mfma_f32_16x16x32_bf16 v[102:105], v[130:133], v[220:223], v[102:105]
	v_mfma_f32_16x16x32_bf16 v[98:101], v[158:161], v[220:223], v[98:101]
	v_mfma_f32_16x16x32_bf16 v[86:89], v[130:133], v[228:231], v[86:89]
	v_mfma_f32_16x16x32_bf16 v[82:85], v[158:161], v[228:231], v[82:85]
	v_mfma_f32_16x16x32_bf16 v[70:73], v[130:133], v[236:239], v[70:73]
	v_mfma_f32_16x16x32_bf16 v[62:65], v[158:161], v[236:239], v[62:65]
	v_mfma_f32_16x16x32_bf16 v[118:121], v[134:137], v[204:207], v[118:121]
	v_mfma_f32_16x16x32_bf16 v[114:117], v[162:165], v[204:207], v[114:117]
	v_mfma_f32_16x16x32_bf16 v[102:105], v[134:137], v[224:227], v[102:105]
	v_mfma_f32_16x16x32_bf16 v[98:101], v[162:165], v[224:227], v[98:101]
	v_mfma_f32_16x16x32_bf16 v[86:89], v[134:137], v[232:235], v[86:89]
	v_mfma_f32_16x16x32_bf16 v[82:85], v[162:165], v[232:235], v[82:85]
	v_mfma_f32_16x16x32_bf16 v[70:73], v[134:137], v[240:243], v[70:73]
	v_mfma_f32_16x16x32_bf16 v[62:65], v[162:165], v[240:243], v[62:65]
	s_setprio 0
	s_setprio 1
	v_mfma_f32_16x16x32_bf16 v[126:129], v[166:169], v[200:203], v[126:129]
	v_mfma_f32_16x16x32_bf16 v[122:125], v[174:177], v[200:203], v[122:125]
	v_mfma_f32_16x16x32_bf16 v[110:113], v[166:169], v[220:223], v[110:113]
	v_mfma_f32_16x16x32_bf16 v[106:109], v[174:177], v[220:223], v[106:109]
	v_mfma_f32_16x16x32_bf16 v[94:97], v[166:169], v[228:231], v[94:97]
	v_mfma_f32_16x16x32_bf16 v[90:93], v[174:177], v[228:231], v[90:93]
	v_mfma_f32_16x16x32_bf16 v[78:81], v[166:169], v[236:239], v[78:81]
	v_mfma_f32_16x16x32_bf16 v[74:77], v[174:177], v[236:239], v[74:77]
	v_mfma_f32_16x16x32_bf16 v[126:129], v[170:173], v[204:207], v[126:129]
	v_mfma_f32_16x16x32_bf16 v[122:125], v[192:195], v[204:207], v[122:125]
	v_mfma_f32_16x16x32_bf16 v[110:113], v[170:173], v[224:227], v[110:113]
	v_mfma_f32_16x16x32_bf16 v[106:109], v[192:195], v[224:227], v[106:109]
	v_mfma_f32_16x16x32_bf16 v[94:97], v[170:173], v[232:235], v[94:97]
	v_mfma_f32_16x16x32_bf16 v[90:93], v[192:195], v[232:235], v[90:93]
	v_mfma_f32_16x16x32_bf16 v[78:81], v[170:173], v[240:243], v[78:81]
	v_mfma_f32_16x16x32_bf16 v[74:77], v[192:195], v[240:243], v[74:77]
	s_setprio 0
	s_barrier
	s_add_i32 s54, s54, s35
	v_lshl_add_u64 v[178:179], s[22:23], 0, v[0:1]
	s_mov_b32 m0, s54
	ds_read_b128 v[200:203], v152 offset:16384
	ds_read_b128 v[204:207], v152 offset:17408
	ds_read_b128 v[220:223], v152 offset:18432
	ds_read_b128 v[224:227], v152 offset:19456
	ds_read_b128 v[228:231], v152 offset:20480
	ds_read_b128 v[232:235], v152 offset:21504
	ds_read_b128 v[236:239], v152 offset:22528
	ds_read_b128 v[240:243], v152 offset:23552
	global_load_lds_dwordx4 v[178:179], off
	s_add_i32 m0, s54, 0x2000
	s_add_u32 s54, s22, 0x40000
	v_lshl_add_u64 v[244:245], s[22:23], 0, v[138:139]
	s_addc_u32 s55, s23, 0
	s_add_i32 s56, s56, s35
	global_load_lds_dwordx4 v[244:245], off
	v_lshl_add_u64 v[246:247], s[54:55], 0, v[0:1]
	s_mov_b32 m0, s56
	v_lshl_add_u64 v[248:249], s[30:31], 0, v[140:141]
	global_load_lds_dwordx4 v[246:247], off
	v_lshl_add_u64 v[246:247], s[54:55], 0, v[138:139]
	s_add_i32 m0, s56, 0x2000
	s_nop 0
	global_load_lds_dwordx4 v[246:247], off
	v_lshl_add_u64 v[246:247], s[30:31], 0, v[142:143]
	s_mov_b32 m0, s37
	s_nop 0
	global_load_lds_dwordx4 v[246:247], off
	s_mov_b32 m0, s38
	s_nop 0
	global_load_lds_dwordx4 v[248:249], off
	s_waitcnt vmcnt(8)
	s_waitcnt lgkmcnt(0)
	s_barrier
; #define PG8_STAGE(bufoff, gbase, voff) do { _Pragma("unroll") for (int _i = 0; _i < 2; ++_i) \
;         __builtin_amdgcn_global_load_lds((const unsigned*)((const char*)(gbase) + (voff)[_i]), (LAS unsigned*)(lds + (bufoff) + ldsw + _i * 8192), 16, 0, 0); } while (0)
; #define PG8_LDA(dst, b, h) do { _Pragma("unroll") for (int m = 0; m < 4; ++m) _Pragma("unroll") for (int k = 0; k < 2; ++k) dst[m][k] = *(const LAS bf16x8*)(lds + PG8_SA(b, h) + aoff + m * 2048 + k * 1024); } while (0)
; #define PG8_LDB(dst, b, h) do { _Pragma("unroll") for (int n = 0; n < 2; ++n) _Pragma("unroll") for (int k = 0; k < 2; ++k) dst[n][k] = *(const LAS bf16x8*)(lds + PG8_SB(b, h) + boff + n * 2048 + k * 1024); } while (0)
; #define PG8_MMA(ai, bj, At, Bt) do { __builtin_amdgcn_s_setprio(1); _Pragma("unroll") for (int m = 0; m < 4; ++m) _Pragma("unroll") for (int n = 0; n < 2; ++n) _Pragma("unroll") for (int k = 0; k < 2; ++k) \
;         acc[ai][bj][m][n] = __builtin_amdgcn_mfma_f32_16x16x32_bf16(Bt[n][k], At[m][k], acc[ai][bj][m][n], 0, 0, 0); __builtin_amdgcn_s_setprio(0); } while (0)
; #define PG8_WAIT_V(n) asm volatile("s_waitcnt vmcnt(" #n ")" ::: "memory")
; #define PG8_WAIT_L(n) asm volatile("s_waitcnt lgkmcnt(" #n ")" ::: "memory")
; #define PG8_BAR __builtin_amdgcn_s_barrier()
; #define PG8_SCHED __builtin_amdgcn_sched_barrier(0)
; template <class Epi>
; __device__ __forceinline__ void gemm_phase(LAS unsigned char* lds, const Gemm g, const Order& S, const Epi& E, const int tid) {
;     ...
;             PG8_WAIT_V(8); PG8_WAIT_L(0); PG8_BAR; PG8_MMA(1, 0, At, B0); PG8_MMA(1, 1, At, B1); PG8_BAR; PG8_SCHED;
;             PG8_LDB(B0, 1, 0); PG8_LDB(B1, 1, 1); PG8_SCHED; PG8_LDA(At, 1, 0); PG8_STAGE(PG8_SA(0, 1), a2 + hstep, voffA);
;             PG8_WAIT_V(8); PG8_WAIT_L(0); PG8_BAR; PG8_MMA(0, 0, At, B0); PG8_MMA(0, 1, At, B1); PG8_BAR; PG8_SCHED;
;             PG8_LDA(At, 1, 1); PG8_STAGE(PG8_SB(1, 0), b3, voffB); PG8_STAGE(PG8_SB(1, 1), b3 + hstep, voffB); PG8_STAGE(PG8_SA(1, 0), a3, voffA);
;             PG8_WAIT_V(8); PG8_WAIT_L(0); PG8_BAR; PG8_MMA(1, 0, At, B0); PG8_MMA(1, 1, At, B1); PG8_BAR; PG8_SCHED;
	s_setprio 1
	s_waitcnt lgkmcnt(0)
	v_mfma_f32_16x16x32_bf16 v[54:57], v[130:133], v[200:203], v[54:57]
	v_mfma_f32_16x16x32_bf16 v[50:53], v[158:161], v[200:203], v[50:53]
	v_mfma_f32_16x16x32_bf16 v[38:41], v[130:133], v[220:223], v[38:41]
	v_mfma_f32_16x16x32_bf16 v[34:37], v[158:161], v[220:223], v[34:37]
	v_mfma_f32_16x16x32_bf16 v[22:25], v[130:133], v[228:231], v[22:25]
	v_mfma_f32_16x16x32_bf16 v[18:21], v[158:161], v[228:231], v[18:21]
	v_mfma_f32_16x16x32_bf16 v[6:9], v[130:133], v[236:239], v[6:9]
	v_mfma_f32_16x16x32_bf16 v[2:5], v[158:161], v[236:239], v[2:5]
	v_mfma_f32_16x16x32_bf16 v[54:57], v[134:137], v[204:207], v[54:57]
	v_mfma_f32_16x16x32_bf16 v[50:53], v[162:165], v[204:207], v[50:53]
	v_mfma_f32_16x16x32_bf16 v[38:41], v[134:137], v[224:227], v[38:41]
	v_mfma_f32_16x16x32_bf16 v[34:37], v[162:165], v[224:227], v[34:37]
	v_mfma_f32_16x16x32_bf16 v[22:25], v[134:137], v[232:235], v[22:25]
	v_mfma_f32_16x16x32_bf16 v[18:21], v[162:165], v[232:235], v[18:21]
	v_mfma_f32_16x16x32_bf16 v[6:9], v[134:137], v[240:243], v[6:9]
	v_mfma_f32_16x16x32_bf16 v[2:5], v[162:165], v[240:243], v[2:5]
	s_setprio 0
	s_setprio 1
	v_mfma_f32_16x16x32_bf16 v[66:69], v[166:169], v[200:203], v[66:69]
	v_mfma_f32_16x16x32_bf16 v[58:61], v[174:177], v[200:203], v[58:61]
	v_mfma_f32_16x16x32_bf16 v[46:49], v[166:169], v[220:223], v[46:49]
	v_mfma_f32_16x16x32_bf16 v[42:45], v[174:177], v[220:223], v[42:45]
	v_mfma_f32_16x16x32_bf16 v[30:33], v[166:169], v[228:231], v[30:33]
	v_mfma_f32_16x16x32_bf16 v[26:29], v[174:177], v[228:231], v[26:29]
	v_mfma_f32_16x16x32_bf16 v[14:17], v[166:169], v[236:239], v[14:17]
	v_mfma_f32_16x16x32_bf16 v[10:13], v[174:177], v[236:239], v[10:13]
	v_mfma_f32_16x16x32_bf16 v[66:69], v[170:173], v[204:207], v[66:69]
	v_mfma_f32_16x16x32_bf16 v[58:61], v[192:195], v[204:207], v[58:61]
	v_mfma_f32_16x16x32_bf16 v[46:49], v[170:173], v[224:227], v[46:49]
	v_mfma_f32_16x16x32_bf16 v[42:45], v[192:195], v[224:227], v[42:45]
	v_mfma_f32_16x16x32_bf16 v[30:33], v[170:173], v[232:235], v[30:33]
	v_mfma_f32_16x16x32_bf16 v[26:29], v[192:195], v[232:235], v[26:29]
	v_mfma_f32_16x16x32_bf16 v[14:17], v[170:173], v[240:243], v[14:17]
	v_mfma_f32_16x16x32_bf16 v[10:13], v[192:195], v[240:243], v[10:13]
	s_setprio 0
	s_barrier
	s_add_i32 s54, 0, 0x18000
	v_add_u32_e32 v153, s54, v156
	s_add_i32 s55, 0, 0x1c000
	ds_read_b128 v[130:133], v153
	ds_read_b128 v[134:137], v153 offset:1024
	ds_read_b128 v[158:161], v153 offset:2048
	ds_read_b128 v[162:165], v153 offset:3072
	v_add_u32_e32 v153, s55, v156
	ds_read_b128 v[166:169], v153
	ds_read_b128 v[170:173], v153 offset:1024
	ds_read_b128 v[174:177], v153 offset:2048
	ds_read_b128 v[192:195], v153 offset:3072
	s_add_u32 s30, s30, 0x40000
	s_addc_u32 s31, s31, 0
	s_mov_b32 m0, s39
	v_lshl_add_u64 v[250:251], s[30:31], 0, v[142:143]
	ds_read_b128 v[200:203], v152 offset:32768
	ds_read_b128 v[204:207], v152 offset:33792
	ds_read_b128 v[220:223], v152 offset:34816
	ds_read_b128 v[224:227], v152 offset:35840
	ds_read_b128 v[228:231], v152 offset:36864
	ds_read_b128 v[232:235], v152 offset:37888
	ds_read_b128 v[236:239], v152 offset:38912
	ds_read_b128 v[240:243], v152 offset:39936
	global_load_lds_dwordx4 v[250:251], off
	v_lshl_add_u64 v[250:251], s[30:31], 0, v[140:141]
	s_mov_b32 m0, s40
	s_nop 0
	global_load_lds_dwordx4 v[250:251], off
	s_waitcnt vmcnt(8)
	s_waitcnt lgkmcnt(0)
	s_barrier
	s_setprio 1
	s_waitcnt lgkmcnt(0)
	v_mfma_f32_16x16x32_bf16 v[118:121], v[130:133], v[200:203], v[118:121]
	v_mfma_f32_16x16x32_bf16 v[114:117], v[158:161], v[200:203], v[114:117]
	v_mfma_f32_16x16x32_bf16 v[102:105], v[130:133], v[220:223], v[102:105]
	v_mfma_f32_16x16x32_bf16 v[98:101], v[158:161], v[220:223], v[98:101]
	v_mfma_f32_16x16x32_bf16 v[86:89], v[130:133], v[228:231], v[86:89]
	v_mfma_f32_16x16x32_bf16 v[82:85], v[158:161], v[228:231], v[82:85]
	v_mfma_f32_16x16x32_bf16 v[70:73], v[130:133], v[236:239], v[70:73]
	v_mfma_f32_16x16x32_bf16 v[62:65], v[158:161], v[236:239], v[62:65]
	v_mfma_f32_16x16x32_bf16 v[118:121], v[134:137], v[204:207], v[118:121]
	v_mfma_f32_16x16x32_bf16 v[114:117], v[162:165], v[204:207], v[114:117]
	v_mfma_f32_16x16x32_bf16 v[102:105], v[134:137], v[224:227], v[102:105]
	v_mfma_f32_16x16x32_bf16 v[98:101], v[162:165], v[224:227], v[98:101]
	v_mfma_f32_16x16x32_bf16 v[86:89], v[134:137], v[232:235], v[86:89]
	v_mfma_f32_16x16x32_bf16 v[82:85], v[162:165], v[232:235], v[82:85]
	v_mfma_f32_16x16x32_bf16 v[70:73], v[134:137], v[240:243], v[70:73]
	v_mfma_f32_16x16x32_bf16 v[62:65], v[162:165], v[240:243], v[62:65]
	s_setprio 0
	s_setprio 1
	v_mfma_f32_16x16x32_bf16 v[126:129], v[166:169], v[200:203], v[126:129]
	v_mfma_f32_16x16x32_bf16 v[122:125], v[174:177], v[200:203], v[122:125]
	v_mfma_f32_16x16x32_bf16 v[110:113], v[166:169], v[220:223], v[110:113]
	v_mfma_f32_16x16x32_bf16 v[106:109], v[174:177], v[220:223], v[106:109]
	v_mfma_f32_16x16x32_bf16 v[94:97], v[166:169], v[228:231], v[94:97]
	v_mfma_f32_16x16x32_bf16 v[90:93], v[174:177], v[228:231], v[90:93]
	v_mfma_f32_16x16x32_bf16 v[78:81], v[166:169], v[236:239], v[78:81]
	v_mfma_f32_16x16x32_bf16 v[74:77], v[174:177], v[236:239], v[74:77]
	v_mfma_f32_16x16x32_bf16 v[126:129], v[170:173], v[204:207], v[126:129]
	v_mfma_f32_16x16x32_bf16 v[122:125], v[192:195], v[204:207], v[122:125]
	v_mfma_f32_16x16x32_bf16 v[110:113], v[170:173], v[224:227], v[110:113]
	v_mfma_f32_16x16x32_bf16 v[106:109], v[192:195], v[224:227], v[106:109]
	v_mfma_f32_16x16x32_bf16 v[94:97], v[170:173], v[232:235], v[94:97]
	v_mfma_f32_16x16x32_bf16 v[90:93], v[192:195], v[232:235], v[90:93]
	v_mfma_f32_16x16x32_bf16 v[78:81], v[170:173], v[240:243], v[78:81]
	v_mfma_f32_16x16x32_bf16 v[74:77], v[192:195], v[240:243], v[74:77]
	s_setprio 0
	s_barrier
; #define PG8_MMA(ai, bj, At, Bt) do { __builtin_amdgcn_s_setprio(1); _Pragma("unroll") for (int m = 0; m < 4; ++m) _Pragma("unroll") for (int n = 0; n < 2; ++n) _Pragma("unroll") for (int k = 0; k < 2; ++k) \
;         acc[ai][bj][m][n] = __builtin_amdgcn_mfma_f32_16x16x32_bf16(Bt[n][k], At[m][k], acc[ai][bj][m][n], 0, 0, 0); __builtin_amdgcn_s_setprio(0); } while (0)
; #define PG8_WAIT_V(n) asm volatile("s_waitcnt vmcnt(" #n ")" ::: "memory")
; #define PG8_WAIT_L(n) asm volatile("s_waitcnt lgkmcnt(" #n ")" ::: "memory")
; #define PG8_BAR __builtin_amdgcn_s_barrier()
; #define PG8_SCHED __builtin_amdgcn_sched_barrier(0)
;     __device__ __forceinline__ void operator()(const f32x4 (&acc)[2][2][4][2], const Unit& u, int wr, int wc, int fr, int fq, float rp0, float rp1, const f32x4& raw0, const f32x4& raw1, float& rn0, float& rn1) const {
;         const int row0 = u.pm * BM + wr * 64 + fr, col0 = u.pn * 128 + wc * 32 + 8 * fq;
;         float rs[8];
; #pragma unroll
;         for (int k = 0; k < 8; ++k) rs[k] = __shfl((k >> 2) ? rp1 : rp0, fr + 16 * (k & 3));
; template <class Epi>
; __device__ __forceinline__ void gemm_phase(LAS unsigned char* lds, const Gemm g, const Order& S, const Epi& E, const int tid) {
;     ...
;             PG8_WAIT_V(8); PG8_WAIT_L(0); PG8_BAR; PG8_MMA(1, 0, At, B0); PG8_MMA(1, 1, At, B1); PG8_BAR; PG8_SCHED;
;         }
;         f32x4 raw0, raw1;
;         if constexpr (Epi::NEEDS_RSTD) { const int rr = (has_next ? nxt.pm : cur.pm) * BM + wr * 64 + fr + 16 * fq;
;             raw0 = *(const f32x4*)(E.ssq + (size_t)rr * 4); raw1 = *(const f32x4*)(E.ssq + (size_t)(rr + HALF) * 4); }
;         if (wr == 0) PG8_BAR;
;         float rn0 = 0.f, rn1 = 0.f;
;         E(acc, cur, wr, wc, fr, fq, rp0, rp1, raw0, raw1, rn0, rn1);
	s_add_i32 s30, s54, s35
	v_lshl_add_u64 v[178:179], v[178:179], 0, s[86:87]
	s_mov_b32 m0, s30
	ds_read_b128 v[200:203], v152 offset:49152
	ds_read_b128 v[204:207], v152 offset:50176
	ds_read_b128 v[220:223], v152 offset:51200
	ds_read_b128 v[224:227], v152 offset:52224
	ds_read_b128 v[228:231], v152 offset:53248
	ds_read_b128 v[232:235], v152 offset:54272
	ds_read_b128 v[236:239], v152 offset:55296
	ds_read_b128 v[240:243], v152 offset:56320
	global_load_lds_dwordx4 v[178:179], off
	s_add_i32 m0, s30, 0x2000
	s_add_u32 s22, s22, 0x40080
	v_lshl_add_u64 v[178:179], v[244:245], 0, s[86:87]
	s_addc_u32 s23, s23, 0
	s_add_i32 s30, s55, s35
	global_load_lds_dwordx4 v[178:179], off
	v_lshl_add_u64 v[178:179], s[22:23], 0, v[0:1]
	s_mov_b32 m0, s30
	s_nop 0
	global_load_lds_dwordx4 v[178:179], off
	v_lshl_add_u64 v[178:179], s[22:23], 0, v[138:139]
	s_add_i32 m0, s30, 0x2000
	s_nop 0
	global_load_lds_dwordx4 v[178:179], off
	v_lshl_add_u64 v[178:179], v[246:247], 0, s[86:87]
	s_mov_b32 m0, s41
	s_nop 0
	global_load_lds_dwordx4 v[178:179], off
	v_lshl_add_u64 v[178:179], v[248:249], 0, s[86:87]
	s_mov_b32 m0, s42
	s_nop 0
	global_load_lds_dwordx4 v[178:179], off
	s_waitcnt vmcnt(8)
	s_waitcnt lgkmcnt(0)
	s_barrier
	s_setprio 1
	s_waitcnt lgkmcnt(0)
	v_mfma_f32_16x16x32_bf16 v[54:57], v[130:133], v[200:203], v[54:57]
	v_mfma_f32_16x16x32_bf16 v[50:53], v[158:161], v[200:203], v[50:53]
	v_mfma_f32_16x16x32_bf16 v[38:41], v[130:133], v[220:223], v[38:41]
	v_mfma_f32_16x16x32_bf16 v[34:37], v[158:161], v[220:223], v[34:37]
	v_mfma_f32_16x16x32_bf16 v[22:25], v[130:133], v[228:231], v[22:25]
	v_mfma_f32_16x16x32_bf16 v[18:21], v[158:161], v[228:231], v[18:21]
	v_mfma_f32_16x16x32_bf16 v[6:9], v[130:133], v[236:239], v[6:9]
	v_mfma_f32_16x16x32_bf16 v[2:5], v[158:161], v[236:239], v[2:5]
	v_mfma_f32_16x16x32_bf16 v[54:57], v[134:137], v[204:207], v[54:57]
	v_mfma_f32_16x16x32_bf16 v[50:53], v[162:165], v[204:207], v[50:53]
	v_mfma_f32_16x16x32_bf16 v[38:41], v[134:137], v[224:227], v[38:41]
	v_mfma_f32_16x16x32_bf16 v[34:37], v[162:165], v[224:227], v[34:37]
	v_mfma_f32_16x16x32_bf16 v[22:25], v[134:137], v[232:235], v[22:25]
	v_mfma_f32_16x16x32_bf16 v[18:21], v[162:165], v[232:235], v[18:21]
	v_mfma_f32_16x16x32_bf16 v[6:9], v[134:137], v[240:243], v[6:9]
	v_mfma_f32_16x16x32_bf16 v[2:5], v[162:165], v[240:243], v[2:5]
	s_setprio 0
	s_setprio 1
	v_mfma_f32_16x16x32_bf16 v[66:69], v[166:169], v[200:203], v[66:69]
	v_mfma_f32_16x16x32_bf16 v[58:61], v[174:177], v[200:203], v[58:61]
	v_mfma_f32_16x16x32_bf16 v[46:49], v[166:169], v[220:223], v[46:49]
	v_mfma_f32_16x16x32_bf16 v[42:45], v[174:177], v[220:223], v[42:45]
	v_mfma_f32_16x16x32_bf16 v[30:33], v[166:169], v[228:231], v[30:33]
	v_mfma_f32_16x16x32_bf16 v[26:29], v[174:177], v[228:231], v[26:29]
	v_mfma_f32_16x16x32_bf16 v[14:17], v[166:169], v[236:239], v[14:17]
	v_mfma_f32_16x16x32_bf16 v[10:13], v[174:177], v[236:239], v[10:13]
	v_mfma_f32_16x16x32_bf16 v[66:69], v[170:173], v[204:207], v[66:69]
	v_mfma_f32_16x16x32_bf16 v[58:61], v[192:195], v[204:207], v[58:61]
	v_mfma_f32_16x16x32_bf16 v[46:49], v[170:173], v[224:227], v[46:49]
	v_mfma_f32_16x16x32_bf16 v[42:45], v[192:195], v[224:227], v[42:45]
	v_mfma_f32_16x16x32_bf16 v[30:33], v[170:173], v[232:235], v[30:33]
	v_mfma_f32_16x16x32_bf16 v[26:29], v[192:195], v[232:235], v[26:29]
	v_mfma_f32_16x16x32_bf16 v[14:17], v[170:173], v[240:243], v[14:17]
	v_mfma_f32_16x16x32_bf16 v[10:13], v[192:195], v[240:243], v[10:13]
	s_setprio 0
	s_barrier
	s_add_i32 s53, s53, 2
	s_add_u32 s26, s26, 0x100
	s_addc_u32 s27, s27, 0
	s_add_u32 s51, s51, 0x100
	s_addc_u32 s52, s52, 0
	s_cmp_gt_u32 s53, 13
	s_cbranch_scc0 .LBB0_319
	v_lshl_add_u32 v130, s48, 8, v150
	v_ashrrev_i32_e32 v131, 31, v130
	v_lshl_add_u64 v[134:135], v[130:131], 4, s[28:29]
	global_load_dwordx4 v[130:133], v[134:135], off
	s_nop 0
	global_load_dwordx4 v[134:137], v[134:135], off offset:2048
	s_andn2_b64 vcc, s[8:9], s[4:5]
	s_and_b64 vcc, exec, vcc
	s_cbranch_vccz .LBB0_322
	s_barrier
.LBB0_322:
	s_andn2_b64 vcc, exec, s[4:5]
	s_mov_b64 s[4:5], -1
	v_and_or_b32 v157, v197, 64, v154
	v_lshlrev_b32_e32 v157, 2, v157
	ds_bpermute_b32 v162, v157, v144
	ds_bpermute_b32 v163, v157, v144 offset:64
	ds_bpermute_b32 v164, v157, v144 offset:128
	ds_bpermute_b32 v165, v157, v144 offset:192
	ds_bpermute_b32 v166, v157, v145
	ds_bpermute_b32 v167, v157, v145 offset:64
	ds_bpermute_b32 v168, v157, v145 offset:128
	ds_bpermute_b32 v169, v157, v145 offset:192
	ds_bpermute_b32 v200, v157, v252
	ds_bpermute_b32 v202, v157, v252 offset:64
	ds_bpermute_b32 v204, v157, v252 offset:128
	ds_bpermute_b32 v206, v157, v252 offset:192
	ds_bpermute_b32 v220, v157, v253
	ds_bpermute_b32 v222, v157, v253 offset:64
	ds_bpermute_b32 v224, v157, v253 offset:128
	ds_bpermute_b32 v226, v157, v253 offset:192
	v_lshl_add_u32 v153, s6, 8, v155
	v_lshl_or_b32 v160, s7, 7, v151
	v_mul_u32_u24_e32 v161, 0x1600, v153
	v_lshl_add_u32 v161, v160, 1, v161
	s_waitcnt lgkmcnt(0)
; __device__ __forceinline__ unsigned pk_bf16(float lo, float hi) { f32x2 v = {lo, hi}; bf16x2_t b = __builtin_convertvector(v, bf16x2_t); return __builtin_bit_cast(unsigned, b); }
; __device__ __forceinline__ float fast_exp2(float x) { return __builtin_amdgcn_exp2f(x); }
; __device__ __forceinline__ float fast_rcp(float x) { return __builtin_amdgcn_rcpf(x); }
;     __device__ __forceinline__ void operator()(const f32x4 (&acc)[2][2][4][2], const Unit& u, int wr, int wc, int fr, int fq, float rp0, float rp1, const f32x4& raw0, const f32x4& raw1, float& rn0, float& rn1) const {
;     ...
;             for (int m = 0; m < 4; ++m) {
;                 const int row = row0 + ai * HALF + m * 16; const float r = rs[ai * 4 + m];
;                 const float c1 = -1.4426950408889634f * r, r2 = r * r;
;                 const f32x4 ga = acc[ai][0][m][0], gb = acc[ai][0][m][1];
;                 const f32x4 ta = ga * c1, tb = gb * c1;
;                 f32x4 ea, eb;
; #pragma unroll
;                 for (int j = 0; j < 4; ++j) { ea[j] = fast_exp2(ta[j]); eb[j] = fast_exp2(tb[j]); }
;                 const f32x4 da = ea + 1.f, db = eb + 1.f;
;                 f32x4 qa, qb;
; #pragma unroll
;                 for (int j = 0; j < 4; ++j) { qa[j] = fast_rcp(da[j]); qb[j] = fast_rcp(db[j]); }
;                 const f32x4 oa = ((ga * acc[ai][1][m][0]) * r2) * qa, ob = ((gb * acc[ai][1][m][1]) * r2) * qb;
;                 u32x4 w;
;                 w.x = pk_bf16(oa[0], oa[1]); w.y = pk_bf16(oa[2], oa[3]); w.z = pk_bf16(ob[0], ob[1]); w.w = pk_bf16(ob[2], ob[3]);
;                 if (ai == 0 && m == 0) rstd_finish(raw0, raw1, rn0, rn1);
;                 *(u32x4*)(O + (size_t)row * FF + col0) = w;
	v_mul_f32_e32 v228, 0xbfb8aa3b, v162
	v_pk_mul_f32 v[126:127], v[118:119], v[126:127]
	v_pk_mul_f32 v[128:129], v[120:121], v[128:129]
	v_pk_mul_f32 v[122:123], v[114:115], v[122:123]
	v_pk_mul_f32 v[124:125], v[116:117], v[124:125]
	v_pk_mul_f32 v[118:119], v[118:119], v[228:229] op_sel_hi:[1,0]
	v_pk_mul_f32 v[120:121], v[120:121], v[228:229] op_sel_hi:[1,0]
	v_pk_mul_f32 v[114:115], v[114:115], v[228:229] op_sel_hi:[1,0]
	v_pk_mul_f32 v[116:117], v[116:117], v[228:229] op_sel_hi:[1,0]
	v_exp_f32_e32 v118, v118
	v_exp_f32_e32 v119, v119
	v_exp_f32_e32 v120, v120
	v_exp_f32_e32 v121, v121
	v_exp_f32_e32 v114, v114
	v_exp_f32_e32 v115, v115
	v_exp_f32_e32 v116, v116
	v_exp_f32_e32 v117, v117
	v_pk_fma_f32 v[118:119], v[118:119], v[200:201], v[200:201] op_sel_hi:[1,0,0]
	v_pk_fma_f32 v[120:121], v[120:121], v[200:201], v[200:201] op_sel_hi:[1,0,0]
	v_pk_fma_f32 v[114:115], v[114:115], v[200:201], v[200:201] op_sel_hi:[1,0,0]
	v_pk_fma_f32 v[116:117], v[116:117], v[200:201], v[200:201] op_sel_hi:[1,0,0]
	v_rcp_f32_e32 v118, v118
	v_rcp_f32_e32 v119, v119
	v_rcp_f32_e32 v120, v120
	v_rcp_f32_e32 v121, v121
	v_rcp_f32_e32 v114, v114
	v_rcp_f32_e32 v115, v115
	v_rcp_f32_e32 v116, v116
	v_rcp_f32_e32 v117, v117
	v_pk_mul_f32 v[126:127], v[126:127], v[118:119]
	v_pk_mul_f32 v[128:129], v[128:129], v[120:121]
	v_pk_mul_f32 v[122:123], v[122:123], v[114:115]
	v_pk_mul_f32 v[124:125], v[124:125], v[116:117]
	v_cvt_pk_bf16_f32 v118, v126, v127
	v_cvt_pk_bf16_f32 v119, v128, v129
	v_cvt_pk_bf16_f32 v120, v122, v123
	v_cvt_pk_bf16_f32 v121, v124, v125
	global_store_dwordx4 v161, v[118:121], s[24:25]
	v_mul_f32_e32 v228, 0xbfb8aa3b, v163
	v_pk_mul_f32 v[110:111], v[102:103], v[110:111]
	v_pk_mul_f32 v[112:113], v[104:105], v[112:113]
	v_pk_mul_f32 v[106:107], v[98:99], v[106:107]
	v_pk_mul_f32 v[108:109], v[100:101], v[108:109]
	v_pk_mul_f32 v[102:103], v[102:103], v[228:229] op_sel_hi:[1,0]
	v_pk_mul_f32 v[104:105], v[104:105], v[228:229] op_sel_hi:[1,0]
	v_pk_mul_f32 v[98:99], v[98:99], v[228:229] op_sel_hi:[1,0]
	v_pk_mul_f32 v[100:101], v[100:101], v[228:229] op_sel_hi:[1,0]
	v_exp_f32_e32 v102, v102
	v_exp_f32_e32 v103, v103
	v_exp_f32_e32 v104, v104
	v_exp_f32_e32 v105, v105
	v_exp_f32_e32 v98, v98
	v_exp_f32_e32 v99, v99
	v_exp_f32_e32 v100, v100
	v_exp_f32_e32 v101, v101
	v_pk_fma_f32 v[102:103], v[102:103], v[202:203], v[202:203] op_sel_hi:[1,0,0]
	v_pk_fma_f32 v[104:105], v[104:105], v[202:203], v[202:203] op_sel_hi:[1,0,0]
	v_pk_fma_f32 v[98:99], v[98:99], v[202:203], v[202:203] op_sel_hi:[1,0,0]
	v_pk_fma_f32 v[100:101], v[100:101], v[202:203], v[202:203] op_sel_hi:[1,0,0]
	v_rcp_f32_e32 v102, v102
	v_rcp_f32_e32 v103, v103
	v_rcp_f32_e32 v104, v104
	v_rcp_f32_e32 v105, v105
	v_rcp_f32_e32 v98, v98
	v_rcp_f32_e32 v99, v99
	v_rcp_f32_e32 v100, v100
	v_rcp_f32_e32 v101, v101
	v_pk_mul_f32 v[110:111], v[110:111], v[102:103]
	v_pk_mul_f32 v[112:113], v[112:113], v[104:105]
	v_pk_mul_f32 v[106:107], v[106:107], v[98:99]
	v_pk_mul_f32 v[108:109], v[108:109], v[100:101]
	v_cvt_pk_bf16_f32 v102, v110, v111
	v_cvt_pk_bf16_f32 v103, v112, v113
	v_cvt_pk_bf16_f32 v104, v106, v107
	v_cvt_pk_bf16_f32 v105, v108, v109
	v_add_u32_e32 v170, 0x16000, v161
	global_store_dwordx4 v170, v[102:105], s[24:25]
	v_mul_f32_e32 v228, 0xbfb8aa3b, v164
	v_pk_mul_f32 v[94:95], v[86:87], v[94:95]
	v_pk_mul_f32 v[96:97], v[88:89], v[96:97]
	v_pk_mul_f32 v[90:91], v[82:83], v[90:91]
	v_pk_mul_f32 v[92:93], v[84:85], v[92:93]
	v_pk_mul_f32 v[86:87], v[86:87], v[228:229] op_sel_hi:[1,0]
	v_pk_mul_f32 v[88:89], v[88:89], v[228:229] op_sel_hi:[1,0]
	v_pk_mul_f32 v[82:83], v[82:83], v[228:229] op_sel_hi:[1,0]
	v_pk_mul_f32 v[84:85], v[84:85], v[228:229] op_sel_hi:[1,0]
	v_exp_f32_e32 v86, v86
	v_exp_f32_e32 v87, v87
	v_exp_f32_e32 v88, v88
	v_exp_f32_e32 v89, v89
	v_exp_f32_e32 v82, v82
	v_exp_f32_e32 v83, v83
	v_exp_f32_e32 v84, v84
	v_exp_f32_e32 v85, v85
	v_pk_fma_f32 v[86:87], v[86:87], v[204:205], v[204:205] op_sel_hi:[1,0,0]
	v_pk_fma_f32 v[88:89], v[88:89], v[204:205], v[204:205] op_sel_hi:[1,0,0]
	v_pk_fma_f32 v[82:83], v[82:83], v[204:205], v[204:205] op_sel_hi:[1,0,0]
	v_pk_fma_f32 v[84:85], v[84:85], v[204:205], v[204:205] op_sel_hi:[1,0,0]
	v_rcp_f32_e32 v86, v86
	v_rcp_f32_e32 v87, v87
	v_rcp_f32_e32 v88, v88
	v_rcp_f32_e32 v89, v89
	v_rcp_f32_e32 v82, v82
	v_rcp_f32_e32 v83, v83
	v_rcp_f32_e32 v84, v84
	v_rcp_f32_e32 v85, v85
	v_pk_mul_f32 v[94:95], v[94:95], v[86:87]
	v_pk_mul_f32 v[96:97], v[96:97], v[88:89]
	v_pk_mul_f32 v[90:91], v[90:91], v[82:83]
	v_pk_mul_f32 v[92:93], v[92:93], v[84:85]
	v_cvt_pk_bf16_f32 v86, v94, v95
	v_cvt_pk_bf16_f32 v87, v96, v97
	v_cvt_pk_bf16_f32 v88, v90, v91
	v_cvt_pk_bf16_f32 v89, v92, v93
	v_add_u32_e32 v170, 0x2c000, v161
	global_store_dwordx4 v170, v[86:89], s[24:25]
	v_mul_f32_e32 v228, 0xbfb8aa3b, v165
	v_pk_mul_f32 v[78:79], v[70:71], v[78:79]
	v_pk_mul_f32 v[80:81], v[72:73], v[80:81]
	v_pk_mul_f32 v[74:75], v[62:63], v[74:75]
	v_pk_mul_f32 v[76:77], v[64:65], v[76:77]
	v_pk_mul_f32 v[70:71], v[70:71], v[228:229] op_sel_hi:[1,0]
	v_pk_mul_f32 v[72:73], v[72:73], v[228:229] op_sel_hi:[1,0]
	v_pk_mul_f32 v[62:63], v[62:63], v[228:229] op_sel_hi:[1,0]
	v_pk_mul_f32 v[64:65], v[64:65], v[228:229] op_sel_hi:[1,0]
	v_exp_f32_e32 v70, v70
	v_exp_f32_e32 v71, v71
	v_exp_f32_e32 v72, v72
	v_exp_f32_e32 v73, v73
	v_exp_f32_e32 v62, v62
	v_exp_f32_e32 v63, v63
	v_exp_f32_e32 v64, v64
	v_exp_f32_e32 v65, v65
	v_pk_fma_f32 v[70:71], v[70:71], v[206:207], v[206:207] op_sel_hi:[1,0,0]
	v_pk_fma_f32 v[72:73], v[72:73], v[206:207], v[206:207] op_sel_hi:[1,0,0]
	v_pk_fma_f32 v[62:63], v[62:63], v[206:207], v[206:207] op_sel_hi:[1,0,0]
; __device__ __forceinline__ unsigned pk_bf16(float lo, float hi) { f32x2 v = {lo, hi}; bf16x2_t b = __builtin_convertvector(v, bf16x2_t); return __builtin_bit_cast(unsigned, b); }
; __device__ __forceinline__ float fast_exp2(float x) { return __builtin_amdgcn_exp2f(x); }
; __device__ __forceinline__ float fast_rcp(float x) { return __builtin_amdgcn_rcpf(x); }
;     __device__ __forceinline__ void operator()(const f32x4 (&acc)[2][2][4][2], const Unit& u, int wr, int wc, int fr, int fq, float rp0, float rp1, const f32x4& raw0, const f32x4& raw1, float& rn0, float& rn1) const {
;     ...
;             for (int m = 0; m < 4; ++m) {
;                 const int row = row0 + ai * HALF + m * 16; const float r = rs[ai * 4 + m];
;                 const float c1 = -1.4426950408889634f * r, r2 = r * r;
;                 const f32x4 ga = acc[ai][0][m][0], gb = acc[ai][0][m][1];
;                 const f32x4 ta = ga * c1, tb = gb * c1;
;                 f32x4 ea, eb;
; #pragma unroll
;                 for (int j = 0; j < 4; ++j) { ea[j] = fast_exp2(ta[j]); eb[j] = fast_exp2(tb[j]); }
;                 const f32x4 da = ea + 1.f, db = eb + 1.f;
;                 f32x4 qa, qb;
; #pragma unroll
;                 for (int j = 0; j < 4; ++j) { qa[j] = fast_rcp(da[j]); qb[j] = fast_rcp(db[j]); }
;                 const f32x4 oa = ((ga * acc[ai][1][m][0]) * r2) * qa, ob = ((gb * acc[ai][1][m][1]) * r2) * qb;
;                 u32x4 w;
;                 w.x = pk_bf16(oa[0], oa[1]); w.y = pk_bf16(oa[2], oa[3]); w.z = pk_bf16(ob[0], ob[1]); w.w = pk_bf16(ob[2], ob[3]);
;                 if (ai == 0 && m == 0) rstd_finish(raw0, raw1, rn0, rn1);
;                 *(u32x4*)(O + (size_t)row * FF + col0) = w;
	v_pk_fma_f32 v[64:65], v[64:65], v[206:207], v[206:207] op_sel_hi:[1,0,0]
	v_rcp_f32_e32 v70, v70
	v_rcp_f32_e32 v71, v71
	v_rcp_f32_e32 v72, v72
	v_rcp_f32_e32 v73, v73
	v_rcp_f32_e32 v62, v62
	v_rcp_f32_e32 v63, v63
	v_rcp_f32_e32 v64, v64
	v_rcp_f32_e32 v65, v65
	v_pk_mul_f32 v[78:79], v[78:79], v[70:71]
	v_pk_mul_f32 v[80:81], v[80:81], v[72:73]
	v_pk_mul_f32 v[74:75], v[74:75], v[62:63]
	v_pk_mul_f32 v[76:77], v[76:77], v[64:65]
	v_cvt_pk_bf16_f32 v70, v78, v79
	v_cvt_pk_bf16_f32 v71, v80, v81
	v_cvt_pk_bf16_f32 v72, v74, v75
	v_cvt_pk_bf16_f32 v73, v76, v77
	v_add_u32_e32 v170, 0x42000, v161
	global_store_dwordx4 v170, v[70:73], s[24:25]
	v_mul_f32_e32 v228, 0xbfb8aa3b, v166
	v_pk_mul_f32 v[66:67], v[54:55], v[66:67]
	v_pk_mul_f32 v[68:69], v[56:57], v[68:69]
	v_pk_mul_f32 v[58:59], v[50:51], v[58:59]
	v_pk_mul_f32 v[60:61], v[52:53], v[60:61]
	v_pk_mul_f32 v[54:55], v[54:55], v[228:229] op_sel_hi:[1,0]
	v_pk_mul_f32 v[56:57], v[56:57], v[228:229] op_sel_hi:[1,0]
	v_pk_mul_f32 v[50:51], v[50:51], v[228:229] op_sel_hi:[1,0]
	v_pk_mul_f32 v[52:53], v[52:53], v[228:229] op_sel_hi:[1,0]
	v_exp_f32_e32 v54, v54
	v_exp_f32_e32 v55, v55
	v_exp_f32_e32 v56, v56
	v_exp_f32_e32 v57, v57
	v_exp_f32_e32 v50, v50
	v_exp_f32_e32 v51, v51
	v_exp_f32_e32 v52, v52
	v_exp_f32_e32 v53, v53
	v_pk_fma_f32 v[54:55], v[54:55], v[220:221], v[220:221] op_sel_hi:[1,0,0]
	v_pk_fma_f32 v[56:57], v[56:57], v[220:221], v[220:221] op_sel_hi:[1,0,0]
	v_pk_fma_f32 v[50:51], v[50:51], v[220:221], v[220:221] op_sel_hi:[1,0,0]
	v_pk_fma_f32 v[52:53], v[52:53], v[220:221], v[220:221] op_sel_hi:[1,0,0]
	v_rcp_f32_e32 v54, v54
	v_rcp_f32_e32 v55, v55
	v_rcp_f32_e32 v56, v56
	v_rcp_f32_e32 v57, v57
	v_rcp_f32_e32 v50, v50
	v_rcp_f32_e32 v51, v51
	v_rcp_f32_e32 v52, v52
	v_rcp_f32_e32 v53, v53
	v_pk_mul_f32 v[66:67], v[66:67], v[54:55]
	v_pk_mul_f32 v[68:69], v[68:69], v[56:57]
	v_pk_mul_f32 v[58:59], v[58:59], v[50:51]
	v_pk_mul_f32 v[60:61], v[60:61], v[52:53]
	v_cvt_pk_bf16_f32 v54, v66, v67
	v_cvt_pk_bf16_f32 v55, v68, v69
	v_cvt_pk_bf16_f32 v56, v58, v59
	v_cvt_pk_bf16_f32 v57, v60, v61
	v_add_u32_e32 v170, 0xb0000, v161
	global_store_dwordx4 v170, v[54:57], s[24:25]
	v_mul_f32_e32 v228, 0xbfb8aa3b, v167
	v_pk_mul_f32 v[46:47], v[38:39], v[46:47]
	v_pk_mul_f32 v[48:49], v[40:41], v[48:49]
	v_pk_mul_f32 v[42:43], v[34:35], v[42:43]
	v_pk_mul_f32 v[44:45], v[36:37], v[44:45]
	v_pk_mul_f32 v[38:39], v[38:39], v[228:229] op_sel_hi:[1,0]
	v_pk_mul_f32 v[40:41], v[40:41], v[228:229] op_sel_hi:[1,0]
	v_pk_mul_f32 v[34:35], v[34:35], v[228:229] op_sel_hi:[1,0]
	v_pk_mul_f32 v[36:37], v[36:37], v[228:229] op_sel_hi:[1,0]
	v_exp_f32_e32 v38, v38
	v_exp_f32_e32 v39, v39
	v_exp_f32_e32 v40, v40
	v_exp_f32_e32 v41, v41
	v_exp_f32_e32 v34, v34
	v_exp_f32_e32 v35, v35
	v_exp_f32_e32 v36, v36
	v_exp_f32_e32 v37, v37
	v_pk_fma_f32 v[38:39], v[38:39], v[222:223], v[222:223] op_sel_hi:[1,0,0]
	v_pk_fma_f32 v[40:41], v[40:41], v[222:223], v[222:223] op_sel_hi:[1,0,0]
	v_pk_fma_f32 v[34:35], v[34:35], v[222:223], v[222:223] op_sel_hi:[1,0,0]
	v_pk_fma_f32 v[36:37], v[36:37], v[222:223], v[222:223] op_sel_hi:[1,0,0]
	v_rcp_f32_e32 v38, v38
	v_rcp_f32_e32 v39, v39
	v_rcp_f32_e32 v40, v40
	v_rcp_f32_e32 v41, v41
	v_rcp_f32_e32 v34, v34
	v_rcp_f32_e32 v35, v35
	v_rcp_f32_e32 v36, v36
	v_rcp_f32_e32 v37, v37
	v_pk_mul_f32 v[46:47], v[46:47], v[38:39]
	v_pk_mul_f32 v[48:49], v[48:49], v[40:41]
	v_pk_mul_f32 v[42:43], v[42:43], v[34:35]
	v_pk_mul_f32 v[44:45], v[44:45], v[36:37]
	v_cvt_pk_bf16_f32 v38, v46, v47
	v_cvt_pk_bf16_f32 v39, v48, v49
	v_cvt_pk_bf16_f32 v40, v42, v43
	v_cvt_pk_bf16_f32 v41, v44, v45
	v_add_u32_e32 v170, 0xc6000, v161
	global_store_dwordx4 v170, v[38:41], s[24:25]
	v_mul_f32_e32 v228, 0xbfb8aa3b, v168
	v_pk_mul_f32 v[30:31], v[22:23], v[30:31]
	v_pk_mul_f32 v[32:33], v[24:25], v[32:33]
	v_pk_mul_f32 v[26:27], v[18:19], v[26:27]
	v_pk_mul_f32 v[28:29], v[20:21], v[28:29]
	v_pk_mul_f32 v[22:23], v[22:23], v[228:229] op_sel_hi:[1,0]
	v_pk_mul_f32 v[24:25], v[24:25], v[228:229] op_sel_hi:[1,0]
	v_pk_mul_f32 v[18:19], v[18:19], v[228:229] op_sel_hi:[1,0]
	v_pk_mul_f32 v[20:21], v[20:21], v[228:229] op_sel_hi:[1,0]
	v_exp_f32_e32 v22, v22
	v_exp_f32_e32 v23, v23
	v_exp_f32_e32 v24, v24
	v_exp_f32_e32 v25, v25
	v_exp_f32_e32 v18, v18
	v_exp_f32_e32 v19, v19
	v_exp_f32_e32 v20, v20
	v_exp_f32_e32 v21, v21
	v_pk_fma_f32 v[22:23], v[22:23], v[224:225], v[224:225] op_sel_hi:[1,0,0]
	v_pk_fma_f32 v[24:25], v[24:25], v[224:225], v[224:225] op_sel_hi:[1,0,0]
	v_pk_fma_f32 v[18:19], v[18:19], v[224:225], v[224:225] op_sel_hi:[1,0,0]
	v_pk_fma_f32 v[20:21], v[20:21], v[224:225], v[224:225] op_sel_hi:[1,0,0]
	v_rcp_f32_e32 v22, v22
	v_rcp_f32_e32 v23, v23
	v_rcp_f32_e32 v24, v24
	v_rcp_f32_e32 v25, v25
	v_rcp_f32_e32 v18, v18
	v_rcp_f32_e32 v19, v19
	v_rcp_f32_e32 v20, v20
	v_rcp_f32_e32 v21, v21
	v_pk_mul_f32 v[30:31], v[30:31], v[22:23]
	v_pk_mul_f32 v[32:33], v[32:33], v[24:25]
	v_pk_mul_f32 v[26:27], v[26:27], v[18:19]
	v_pk_mul_f32 v[28:29], v[28:29], v[20:21]
	v_cvt_pk_bf16_f32 v22, v30, v31
	v_cvt_pk_bf16_f32 v23, v32, v33
	v_cvt_pk_bf16_f32 v24, v26, v27
	v_cvt_pk_bf16_f32 v25, v28, v29
	v_add_u32_e32 v170, 0xdc000, v161
	global_store_dwordx4 v170, v[22:25], s[24:25]
	v_mul_f32_e32 v228, 0xbfb8aa3b, v169
	v_pk_mul_f32 v[14:15], v[6:7], v[14:15]
	v_pk_mul_f32 v[16:17], v[8:9], v[16:17]
	v_pk_mul_f32 v[10:11], v[2:3], v[10:11]
	v_pk_mul_f32 v[12:13], v[4:5], v[12:13]
	v_pk_mul_f32 v[6:7], v[6:7], v[228:229] op_sel_hi:[1,0]
	v_pk_mul_f32 v[8:9], v[8:9], v[228:229] op_sel_hi:[1,0]
	v_pk_mul_f32 v[2:3], v[2:3], v[228:229] op_sel_hi:[1,0]
	v_pk_mul_f32 v[4:5], v[4:5], v[228:229] op_sel_hi:[1,0]
	v_exp_f32_e32 v6, v6
	v_exp_f32_e32 v7, v7
	v_exp_f32_e32 v8, v8
	v_exp_f32_e32 v9, v9
	v_exp_f32_e32 v2, v2
	v_exp_f32_e32 v3, v3
	v_exp_f32_e32 v4, v4
	v_exp_f32_e32 v5, v5
	v_pk_fma_f32 v[6:7], v[6:7], v[226:227], v[226:227] op_sel_hi:[1,0,0]
	v_pk_fma_f32 v[8:9], v[8:9], v[226:227], v[226:227] op_sel_hi:[1,0,0]
	v_pk_fma_f32 v[2:3], v[2:3], v[226:227], v[226:227] op_sel_hi:[1,0,0]
	v_pk_fma_f32 v[4:5], v[4:5], v[226:227], v[226:227] op_sel_hi:[1,0,0]
	v_rcp_f32_e32 v6, v6
	v_rcp_f32_e32 v7, v7
	v_rcp_f32_e32 v8, v8
	v_rcp_f32_e32 v9, v9
	v_rcp_f32_e32 v2, v2
	v_rcp_f32_e32 v3, v3
	v_rcp_f32_e32 v4, v4
	v_rcp_f32_e32 v5, v5
	v_pk_mul_f32 v[14:15], v[14:15], v[6:7]
	v_pk_mul_f32 v[16:17], v[16:17], v[8:9]
	v_pk_mul_f32 v[10:11], v[10:11], v[2:3]
	v_pk_mul_f32 v[12:13], v[12:13], v[4:5]
	v_cvt_pk_bf16_f32 v6, v14, v15
	v_cvt_pk_bf16_f32 v7, v16, v17
	v_cvt_pk_bf16_f32 v8, v10, v11
	v_cvt_pk_bf16_f32 v9, v12, v13
	v_add_u32_e32 v170, 0xf2000, v161
	global_store_dwordx4 v170, v[6:9], s[24:25]
	s_waitcnt vmcnt(8)
; #define PG8_BAR __builtin_amdgcn_s_barrier()
; __device__ __forceinline__ void rstd_finish(const f32x4& raw0, const f32x4& raw1, float& rn0, float& rn1) {
;     rn0 = rsqrtf(((raw0.x + raw0.y) + (raw0.z + raw0.w)) * (1.f / DM) + EPS); rn1 = rsqrtf(((raw1.x + raw1.y) + (raw1.z + raw1.w)) * (1.f / DM) + EPS);
;     asm volatile("" :: "v"(rn0), "v"(rn1) : "memory");
; template <class Epi>
; __device__ __forceinline__ void gemm_phase(LAS unsigned char* lds, const Gemm g, const Order& S, const Epi& E, const int tid) {
;     ...
;         if constexpr (Epi::NEEDS_RSTD && !Epi::EARLY_RSTD) rstd_finish(raw0, raw1, rn0, rn1);
;         rp0 = rn0; rp1 = rn1;
;         if (!has_next) break;
; #pragma unroll
;         for (int a = 0; a < 2; ++a)
; #pragma unroll
;             for (int b = 0; b < 2; ++b)
; #pragma unroll
;                 for (int m = 0; m < 4; ++m)
; #pragma unroll
;                     for (int n = 0; n < 2; ++n) { double zl, zh; asm volatile("v_mov_b64 %0, 0\n\tv_mov_b64 %1, 0" : "=v"(zl), "=v"(zh)); d64x2 zz = {zl, zh}; acc[a][b][m][n] = __builtin_bit_cast(f32x4, zz); }
;         cur = nxt; cA = nA; cB = nB; ++ui;
;         if (wr == 1) PG8_BAR;
	v_mov_b32_e32 v122, v135
	v_mov_b32_e32 v123, v136
	v_mov_b32_e32 v135, v137
	v_mov_b32_e32 v124, v131
	v_mov_b32_e32 v125, v132
	v_mov_b32_e32 v131, v133
	v_pk_add_f32 v[122:123], v[122:123], v[134:135]
	v_pk_add_f32 v[124:125], v[124:125], v[130:131]
	v_mov_b32_e32 v126, v124
	v_mov_b32_e32 v127, v122
	v_mov_b32_e32 v122, v125
	v_pk_add_f32 v[122:123], v[126:127], v[122:123]
	v_pk_fma_f32 v[122:123], v[122:123], s[84:85], v[182:183] op_sel_hi:[1,0,0]
	v_mov_b32_e32 v252, v122
	v_mov_b32_e32 v253, v123
	v_mul_f32_e32 v119, 0x4b800000, v123
	v_mul_f32_e32 v118, 0x4b800000, v122
	v_cmp_gt_f32_e64 s[100:101], s89, v123
	v_cmp_gt_f32_e64 s[6:7], s89, v122
	s_nop 1
	v_cndmask_b32_e64 v119, v123, v119, s[100:101]
	v_cndmask_b32_e64 v118, v122, v118, s[6:7]
	v_rsq_f32_e32 v123, v119
	v_rsq_f32_e32 v122, v118
	s_nop 0
	v_pk_mul_f32 v[120:121], v[122:123], s[78:79] op_sel_hi:[1,0]
	v_cndmask_b32_e64 v145, v123, v121, s[100:101]
	v_cndmask_b32_e64 v144, v122, v120, s[6:7]
	s_cbranch_vccnz .LBB0_315
	s_andn2_b64 vcc, exec, s[2:3]
	s_cbranch_vccnz .LBB0_314
	s_nop 0
	s_branch .LBB0_314
